# v9a + attention phase: static priority raised for the other wave half (waves 4-7) instead of waves 0-3
# speedup vs baseline: 1.0162x; 1.0162x over previous
; __device__ __forceinline__ int opaque_tid(int wv) { int l; asm volatile("v_mbcnt_lo_u32_b32 %0, -1, 0\n\tv_mbcnt_hi_u32_b32 %0, -1, %0" : "=v"(l)); return wv * 64 + l; }
;     __device__ __forceinline__ const float* in(int i) const { return *(const float* const CAS*)(base() + 8 * i); }
; __device__ __forceinline__ float uniform_f(float v) { return __int_as_float(__builtin_amdgcn_readfirstlane(__float_as_int(v))); }
; __device__ __forceinline__ void attn_phase(LAS unsigned char* lds, const KArgs& P, int G, int c, int wv) {
;     ...
;     const int tid = opaque_tid(wv), wid = __builtin_amdgcn_readfirstlane(tid >> 6), lane = tid & 63, r = lane & 31, hh = lane >> 5;
;     const int sub = wid >> 2, wq = wid & 3;
;     float lamv, Mb;
;     { const float* gq = P.in(I_GQ); const float* gk = P.in(I_GK);
;       float d1 = P.in(I_LQ1)[lane] * P.in(I_LK1)[lane] + P.in(I_LQ1)[lane + 64] * P.in(I_LK1)[lane + 64];
;       float d2 = P.in(I_LQ2)[lane] * P.in(I_LK2)[lane] + P.in(I_LQ2)[lane + 64] * P.in(I_LK2)[lane + 64];
;       float mq = fmaxf(fabsf(gq[lane]), fabsf(gq[lane + 64])), mk = fmaxf(fabsf(gk[lane]), fabsf(gk[lane + 64]));
; #pragma unroll
;       for (int o = 32; o >= 1; o >>= 1) { d1 += __shfl_xor(d1, o); d2 += __shfl_xor(d2, o); mq = fmaxf(mq, __shfl_xor(mq, o)); mk = fmaxf(mk, __shfl_xor(mk, o)); }
;       lamv = uniform_f(__expf(d1) - __expf(d2) + 0.2f);
;       Mb = uniform_f(11.313708498984761f * LOG2E * mq * mk * 1.01f + 0.5f); }
;     const int pr = (r & 19) | ((r & 4) << 1) | ((r & 8) >> 1);
;     if (sub == 0) __builtin_amdgcn_s_setprio(1); else __builtin_amdgcn_s_setprio(0);
.LBB0_318:
	s_mov_b64 s[4:5], s[0:1]
	s_waitcnt lgkmcnt(0)
	s_barrier
	s_load_dwordx2 s[54:55], s[4:5], 0xe0
	s_mov_b64 s[4:5], s[0:1]
	s_load_dwordx2 s[18:19], s[4:5], 0xe0
	s_mov_b64 s[4:5], s[0:1]
	s_load_dwordx2 s[56:57], s[4:5], 0xe0
	s_mov_b64 s[4:5], s[0:1]
	v_mbcnt_lo_u32_b32 v0, -1, 0
	v_mbcnt_hi_u32_b32 v0, -1, v0
	s_mov_b64 s[6:7], s[0:1]
	s_load_dwordx2 s[4:5], s[4:5], 0x30
	s_mov_b64 s[8:9], s[0:1]
	s_load_dwordx2 s[6:7], s[6:7], 0x38
	s_load_dwordx2 s[8:9], s[8:9], 0x40
	v_and_b32_e32 v246, 63, v0
	v_lshlrev_b32_e32 v1, 2, v246
	v_mbcnt_hi_u32_b32 v247, -1, v182
	v_and_b32_e32 v13, 64, v247
	s_waitcnt lgkmcnt(0)
	global_load_dword v2, v1, s[8:9]
	s_mov_b64 s[8:9], s[0:1]
	s_load_dwordx2 s[8:9], s[8:9], 0x48
	v_xor_b32_e32 v14, 32, v247
	v_add_u32_e32 v13, 64, v13
	v_cmp_lt_i32_e32 vcc, v14, v13
	v_xor_b32_e32 v15, 16, v247
	s_waitcnt lgkmcnt(0)
	global_load_dword v3, v1, s[8:9]
	s_mov_b64 s[8:9], s[0:1]
	s_load_dwordx2 s[8:9], s[8:9], 0x40
	v_cndmask_b32_e32 v14, v247, v14, vcc
	v_lshlrev_b32_e32 v244, 2, v14
	v_cmp_lt_i32_e32 vcc, v15, v13
	v_xor_b32_e32 v16, 8, v247
	s_waitcnt lgkmcnt(0)
	global_load_dword v4, v1, s[8:9] offset:256
	s_mov_b64 s[8:9], s[0:1]
	s_load_dwordx2 s[8:9], s[8:9], 0x48
	v_cndmask_b32_e32 v15, v247, v15, vcc
	v_lshlrev_b32_e32 v245, 2, v15
	v_cmp_lt_i32_e32 vcc, v16, v13
	v_xor_b32_e32 v17, 4, v247
	s_waitcnt lgkmcnt(0)
	global_load_dword v5, v1, s[8:9] offset:256
	s_mov_b64 s[8:9], s[0:1]
	s_load_dwordx2 s[8:9], s[8:9], 0x50
	v_cndmask_b32_e32 v16, v247, v16, vcc
	v_lshlrev_b32_e32 v14, 2, v16
	v_cmp_lt_i32_e32 vcc, v17, v13
	v_xor_b32_e32 v18, 2, v247
	s_waitcnt lgkmcnt(0)
	global_load_dword v6, v1, s[8:9]
	s_mov_b64 s[8:9], s[0:1]
	s_load_dwordx2 s[8:9], s[8:9], 0x58
	v_cndmask_b32_e32 v17, v247, v17, vcc
	v_cmp_lt_i32_e32 vcc, v18, v13
	v_xor_b32_e32 v19, 1, v247
	v_add_u32_e32 v0, s90, v0
	s_waitcnt lgkmcnt(0)
	global_load_dword v7, v1, s[8:9]
	s_mov_b64 s[8:9], s[0:1]
	s_load_dwordx2 s[8:9], s[8:9], 0x50
	v_cndmask_b32_e32 v18, v247, v18, vcc
	v_cmp_lt_i32_e32 vcc, v19, v13
	s_mov_b64 s[16:17], -1
	s_waitcnt lgkmcnt(0)
	global_load_dword v8, v1, s[8:9] offset:256
	s_mov_b64 s[8:9], s[0:1]
	s_load_dwordx2 s[8:9], s[8:9], 0x58
	global_load_dword v9, v1, s[4:5] offset:256
	global_load_dword v10, v1, s[4:5]
	global_load_dword v11, v1, s[6:7]
	s_waitcnt lgkmcnt(0)
	global_load_dword v12, v1, s[8:9] offset:256
	s_nop 0
	global_load_dword v1, v1, s[6:7] offset:256
	v_cndmask_b32_e32 v13, v247, v19, vcc
	v_lshlrev_b32_e32 v13, 2, v13
	v_readfirstlane_b32 s4, v0
	s_cmpk_lt_u32 s4, 0x100
	s_cselect_b64 s[20:21], -1, 0
	s_cmpk_gt_u32 s4, 0xff
	s_waitcnt vmcnt(8)
	v_mul_f32_e32 v4, v4, v5
	v_fmac_f32_e32 v4, v2, v3
	ds_bpermute_b32 v2, v244, v4
	v_lshlrev_b32_e32 v3, 2, v17
	v_lshlrev_b32_e32 v5, 2, v18
	s_waitcnt lgkmcnt(0)
	v_add_f32_e32 v2, v4, v2
	ds_bpermute_b32 v4, v245, v2
	s_waitcnt lgkmcnt(0)
	v_add_f32_e32 v2, v2, v4
	ds_bpermute_b32 v4, v14, v2
	s_waitcnt lgkmcnt(0)
	v_add_f32_e32 v2, v2, v4
	s_waitcnt vmcnt(4)
	v_max_f32_e64 v9, |v9|, |v9|
	s_waitcnt vmcnt(3)
	v_max_f32_e64 v10, |v10|, |v10|
	v_max_f32_e32 v9, v10, v9
	ds_bpermute_b32 v4, v244, v9
	ds_bpermute_b32 v10, v3, v2
	s_waitcnt vmcnt(2)
	v_max_f32_e64 v11, |v11|, |v11|
	s_waitcnt vmcnt(0)
	v_max_f32_e64 v1, |v1|, |v1|
	v_mul_f32_e32 v8, v8, v12
	v_max_f32_e32 v1, v11, v1
	s_waitcnt lgkmcnt(1)
	v_max_f32_e32 v4, v4, v4
	v_fmac_f32_e32 v8, v6, v7
	ds_bpermute_b32 v7, v244, v1
	v_max_f32_e32 v4, v9, v4
	s_waitcnt lgkmcnt(1)
	v_add_f32_e32 v2, v2, v10
	ds_bpermute_b32 v6, v244, v8
	ds_bpermute_b32 v9, v245, v4
	ds_bpermute_b32 v10, v5, v2
	s_waitcnt lgkmcnt(3)
	v_max_f32_e32 v7, v7, v7
	v_max_f32_e32 v1, v1, v7
	s_waitcnt lgkmcnt(2)
	v_add_f32_e32 v6, v8, v6
	s_waitcnt lgkmcnt(1)
	v_max_f32_e32 v8, v9, v9
	s_waitcnt lgkmcnt(0)
	v_add_f32_e32 v2, v2, v10
	ds_bpermute_b32 v7, v245, v6
	ds_bpermute_b32 v10, v245, v1
	v_max_f32_e32 v4, v4, v8
	ds_bpermute_b32 v9, v13, v2
	ds_bpermute_b32 v8, v14, v4
	s_waitcnt lgkmcnt(3)
	v_add_f32_e32 v6, v6, v7
	s_waitcnt lgkmcnt(2)
	v_max_f32_e32 v7, v10, v10
	v_max_f32_e32 v1, v1, v7
	s_waitcnt lgkmcnt(1)
	v_add_f32_e32 v2, v2, v9
	ds_bpermute_b32 v9, v14, v6
	s_waitcnt lgkmcnt(1)
	v_max_f32_e32 v7, v8, v8
	ds_bpermute_b32 v8, v14, v1
	v_max_f32_e32 v4, v4, v7
	ds_bpermute_b32 v7, v3, v4
	s_waitcnt lgkmcnt(2)
	v_add_f32_e32 v6, v6, v9
	ds_bpermute_b32 v9, v3, v6
	s_waitcnt lgkmcnt(2)
	v_max_f32_e32 v8, v8, v8
	v_max_f32_e32 v1, v1, v8
	s_waitcnt lgkmcnt(1)
	v_max_f32_e32 v7, v7, v7
	ds_bpermute_b32 v3, v3, v1
	v_max_f32_e32 v4, v4, v7
	ds_bpermute_b32 v7, v5, v4
	s_waitcnt lgkmcnt(2)
	v_add_f32_e32 v6, v6, v9
	ds_bpermute_b32 v8, v5, v6
	s_waitcnt lgkmcnt(2)
	v_max_f32_e32 v3, v3, v3
	v_max_f32_e32 v1, v1, v3
	s_waitcnt lgkmcnt(1)
	v_max_f32_e32 v3, v7, v7
	v_max_f32_e32 v3, v4, v3
	ds_bpermute_b32 v4, v5, v1
	s_waitcnt lgkmcnt(1)
	v_add_f32_e32 v5, v6, v8
	ds_bpermute_b32 v6, v13, v3
	ds_bpermute_b32 v7, v13, v5
	v_mul_f32_e32 v2, 0x3fb8aa3b, v2
	s_waitcnt lgkmcnt(2)
	v_max_f32_e32 v4, v4, v4
	v_max_f32_e32 v1, v1, v4
	s_waitcnt lgkmcnt(1)
	v_max_f32_e32 v4, v6, v6
	ds_bpermute_b32 v6, v13, v1
	s_waitcnt lgkmcnt(1)
	v_add_f32_e32 v5, v5, v7
	v_max_f32_e32 v3, v3, v4
	v_mul_f32_e32 v4, 0x3fb8aa3b, v5
	v_exp_f32_e32 v2, v2
	v_exp_f32_e32 v4, v4
	s_waitcnt lgkmcnt(0)
	v_max_f32_e32 v5, v6, v6
	v_mul_f32_e32 v3, 0x418293ee, v3
	v_max_f32_e32 v1, v1, v5
	v_sub_f32_e32 v2, v2, v4
	v_mul_f32_e32 v1, v1, v3
	v_readfirstlane_b32 s5, v2
	v_readfirstlane_b32 s6, v1
	s_cbranch_scc0 .LBB0_320
	s_setprio 1
	s_mov_b64 s[16:17], 0
.LBB0_320:
	s_andn2_b64 vcc, exec, s[16:17]
	s_cbranch_vccnz .LBB0_322
	s_setprio 0
